# SEAM 5 in the count-in form of SB1 (per-XCD count with return, last arriver writes back, flat poll): no census loop, no per-XCD release hop
# speedup vs baseline: 1.0335x; 1.0065x over previous
.Lsb1_census_ok:
	v_readlane_b32 s18, v4, s33
	s_nop 3
	v_writelane_b32 v246, s18, 8
	v_readfirstlane_b32 s19, v3
	s_add_u32 s19, s19, 1
	s_cmp_lg_u32 s19, s18
	s_cbranch_scc1 .Lsb1_arr_end
	buffer_wbl2 sc1
	s_waitcnt vmcnt(0)
	s_add_u32 s8, s92, 0x57000
	s_addc_u32 s9, s93, 0
	v_mov_b32_e32 v3, s18
	global_atomic_add v2, v3, s[8:9]

.LBB0_556:
	s_cmp_gt_i32 s95, 6
	s_cselect_b64 s[0:1], -1, 0
	s_and_b64 s[4:5], s[58:59], s[0:1]
	s_andn2_b64 vcc, exec, s[4:5]
	s_cbranch_vccnz .LBB0_610
	s_waitcnt vmcnt(0) lgkmcnt(0)
	s_barrier
	s_mov_b64 s[4:5], exec
	v_readlane_b32 s6, v246, 2
	v_readlane_b32 s7, v246, 3
	s_and_b64 s[6:7], s[4:5], s[6:7]
	s_mov_b64 exec, s[6:7]
	s_cbranch_execz .Lsb5_end
	s_lshl_b32 s8, s33, 8
	s_add_u32 s8, s8, 0x56080
	s_add_u32 s8, s92, s8
	s_addc_u32 s9, s93, 0
	v_mov_b32_e32 v2, 0
	v_mov_b32_e32 v3, 1
	global_atomic_add v3, v2, v3, s[8:9] sc0
	s_add_u32 s8, s92, 0x57100
	s_addc_u32 s9, s93, 0
	v_readlane_b32 s18, v246, 8
	s_waitcnt vmcnt(0)
	v_readfirstlane_b32 s19, v3
	s_add_u32 s19, s19, 1
	s_cmp_lg_u32 s19, s18
	s_cbranch_scc1 .Lsb5_poll0
	buffer_wbl2 sc1
	s_waitcnt vmcnt(0)
	v_mov_b32_e32 v3, s18
	global_atomic_add v2, v3, s[8:9]
.Lsb5_poll0:
	buffer_inv sc1
	s_mov_b32 s10, 0x400000
	s_movk_i32 s11, 0xff
.Lsb5_poll:
	global_load_dword v3, v2, s[8:9] sc1
	s_waitcnt vmcnt(0)
	v_cmp_lt_u32_e32 vcc, s11, v3
	s_cbranch_vccnz .Lsb5_end
	s_sleep 1
	s_sub_u32 s10, s10, 1
	s_cmp_lg_u32 s10, 0
	s_cbranch_scc1 .Lsb5_poll
.Lsb5_end:
	s_mov_b64 exec, s[4:5]
	s_barrier
